# tile header: accumulator zeroing with 64-bit moves (half the VALU instructions)
# baseline (speedup 1.0000x reference)
.LBB0_146:
	s_ashr_i32 s11, s10, 31
	v_cmp_lt_i64_e32 vcc, s[12:13], v[140:141]
	s_lshl_b64 s[12:13], s[10:11], 20
	s_add_u32 s12, s80, s12
	s_addc_u32 s13, s81, s13
	s_and_b64 s[14:15], vcc, exec
	s_cselect_b32 s11, s13, s17
	s_cselect_b32 s41, s12, s16
	s_ashr_i32 s9, s8, 31
	s_lshl_b64 s[14:15], s[8:9], 20
	s_add_u32 s14, s22, s14
	s_addc_u32 s15, s23, s15
	s_and_b64 s[20:21], vcc, exec
	s_cselect_b32 s9, s15, s19
	s_cselect_b32 s44, s14, s18
	s_add_u32 s16, s16, 0x80080
	s_addc_u32 s17, s17, 0
	s_add_u32 s45, s18, 0x100
	v_mov_b32_e32 v0, 0
	s_addc_u32 s46, s19, 0
	s_mov_b32 s47, -2
	v_mov_b32_e32 v1, v0
	v_mov_b64_e32 v[2:3], 0
	v_mov_b64_e32 v[4:5], 0
	v_mov_b64_e32 v[6:7], 0
	v_mov_b64_e32 v[16:17], 0
	s_waitcnt vmcnt(0)
	v_mov_b64_e32 v[18:19], 0
	v_mov_b64_e32 v[20:21], 0
	v_mov_b64_e32 v[22:23], 0
	v_mov_b64_e32 v[32:33], 0
	v_mov_b64_e32 v[34:35], 0
	v_mov_b64_e32 v[36:37], 0
	v_mov_b64_e32 v[38:39], 0
	v_mov_b64_e32 v[48:49], 0
	v_mov_b64_e32 v[50:51], 0
	v_mov_b64_e32 v[52:53], 0
	v_mov_b64_e32 v[54:55], 0
	v_mov_b64_e32 v[8:9], 0
	v_mov_b64_e32 v[10:11], 0
	v_mov_b64_e32 v[12:13], 0
	v_mov_b64_e32 v[14:15], 0
	v_mov_b64_e32 v[24:25], 0
	v_mov_b64_e32 v[26:27], 0
	v_mov_b64_e32 v[28:29], 0
	v_mov_b64_e32 v[30:31], 0
	v_mov_b64_e32 v[40:41], 0
	v_mov_b64_e32 v[42:43], 0
	v_mov_b64_e32 v[44:45], 0
	v_mov_b64_e32 v[46:47], 0
	v_mov_b64_e32 v[56:57], 0
	v_mov_b64_e32 v[58:59], 0
	v_mov_b64_e32 v[60:61], 0
	v_mov_b64_e32 v[62:63], 0
	v_mov_b64_e32 v[64:65], 0
	v_mov_b64_e32 v[66:67], 0
	v_mov_b64_e32 v[68:69], 0
	v_mov_b64_e32 v[70:71], 0
	v_mov_b64_e32 v[80:81], 0
	v_mov_b64_e32 v[82:83], 0
	v_mov_b64_e32 v[84:85], 0
	v_mov_b64_e32 v[86:87], 0
	v_mov_b64_e32 v[96:97], 0
	v_mov_b64_e32 v[98:99], 0
	v_mov_b64_e32 v[100:101], 0
	v_mov_b64_e32 v[102:103], 0
	v_mov_b64_e32 v[112:113], 0
	v_mov_b64_e32 v[114:115], 0
	v_mov_b64_e32 v[116:117], 0
	v_mov_b64_e32 v[118:119], 0
	v_mov_b64_e32 v[72:73], 0
	v_mov_b64_e32 v[74:75], 0
	v_mov_b64_e32 v[76:77], 0
	v_mov_b64_e32 v[78:79], 0
	v_mov_b64_e32 v[88:89], 0
	v_mov_b64_e32 v[90:91], 0
	v_mov_b64_e32 v[92:93], 0
	v_mov_b64_e32 v[94:95], 0
	v_mov_b64_e32 v[104:105], 0
	v_mov_b64_e32 v[106:107], 0
	v_mov_b64_e32 v[108:109], 0
	v_mov_b64_e32 v[110:111], 0
	v_mov_b64_e32 v[120:121], 0
	v_mov_b64_e32 v[122:123], 0
	v_mov_b64_e32 v[124:125], 0
	v_mov_b64_e32 v[126:127], 0
	v_xor_b32_e32 v220, 64, v165
	v_xor_b32_e32 v221, 64, v166
	v_xor_b32_e32 v234, 64, v167
	v_add_u32_e32 v235, 0x18000, v161
	v_xor_b32_e32 v236, 64, v235

.LBB0_282:
	s_ashr_i32 s11, s10, 31
	s_lshl_b64 s[16:17], s[10:11], 20
	s_add_u32 s16, s22, s16
	s_addc_u32 s17, s23, s17
	s_and_b64 s[6:7], s[6:7], exec
	s_cselect_b32 s1, s17, s19
	s_cselect_b32 s11, s16, s18
	s_add_u32 s6, s20, 0x180080
	s_addc_u32 s7, s21, 0
	s_add_u32 s43, s18, 0x100
	v_mov_b32_e32 v0, 0
	s_addc_u32 s44, s19, 0
	s_mov_b32 s45, -2
	s_waitcnt lgkmcnt(0)
	v_mov_b32_e32 v1, v0
	v_mov_b64_e32 v[2:3], 0
	v_mov_b64_e32 v[4:5], 0
	v_mov_b64_e32 v[6:7], 0
	s_waitcnt vmcnt(0)
	v_mov_b64_e32 v[16:17], 0
	v_mov_b64_e32 v[18:19], 0
	v_mov_b64_e32 v[20:21], 0
	v_mov_b64_e32 v[22:23], 0
	v_mov_b64_e32 v[32:33], 0
	v_mov_b64_e32 v[34:35], 0
	v_mov_b64_e32 v[36:37], 0
	v_mov_b64_e32 v[38:39], 0
	v_mov_b64_e32 v[48:49], 0
	v_mov_b64_e32 v[50:51], 0
	v_mov_b64_e32 v[52:53], 0
	v_mov_b64_e32 v[54:55], 0
	v_mov_b64_e32 v[8:9], 0
	v_mov_b64_e32 v[10:11], 0
	v_mov_b64_e32 v[12:13], 0
	v_mov_b64_e32 v[14:15], 0
	v_mov_b64_e32 v[24:25], 0
	v_mov_b64_e32 v[26:27], 0
	v_mov_b64_e32 v[28:29], 0
	v_mov_b64_e32 v[30:31], 0
	v_mov_b64_e32 v[40:41], 0
	v_mov_b64_e32 v[42:43], 0
	v_mov_b64_e32 v[44:45], 0
	v_mov_b64_e32 v[46:47], 0
	v_mov_b64_e32 v[56:57], 0
	v_mov_b64_e32 v[58:59], 0
	v_mov_b64_e32 v[60:61], 0
	v_mov_b64_e32 v[62:63], 0
	v_mov_b64_e32 v[64:65], 0
	v_mov_b64_e32 v[66:67], 0
	v_mov_b64_e32 v[68:69], 0
	v_mov_b64_e32 v[70:71], 0
	v_mov_b64_e32 v[80:81], 0
	v_mov_b64_e32 v[82:83], 0
	v_mov_b64_e32 v[84:85], 0
	v_mov_b64_e32 v[86:87], 0
	v_mov_b64_e32 v[96:97], 0
	v_mov_b64_e32 v[98:99], 0
	v_mov_b64_e32 v[100:101], 0
	v_mov_b64_e32 v[102:103], 0
	v_mov_b64_e32 v[112:113], 0
	v_mov_b64_e32 v[114:115], 0
	v_mov_b64_e32 v[116:117], 0
	v_mov_b64_e32 v[118:119], 0
	v_mov_b64_e32 v[72:73], 0
	v_mov_b64_e32 v[74:75], 0
	v_mov_b64_e32 v[76:77], 0
	v_mov_b64_e32 v[78:79], 0
	v_mov_b64_e32 v[88:89], 0
	v_mov_b64_e32 v[90:91], 0
	v_mov_b64_e32 v[92:93], 0
	v_mov_b64_e32 v[94:95], 0
	v_mov_b64_e32 v[104:105], 0
	v_mov_b64_e32 v[106:107], 0
	v_mov_b64_e32 v[108:109], 0
	v_mov_b64_e32 v[110:111], 0
	v_mov_b64_e32 v[120:121], 0
	v_mov_b64_e32 v[122:123], 0
	v_mov_b64_e32 v[124:125], 0
	v_mov_b64_e32 v[126:127], 0
	v_xor_b32_e32 v150, 64, v146
	v_xor_b32_e32 v151, 64, v147
	v_xor_b32_e32 v216, 64, v148
	v_add_u32_e32 v217, 0x18000, v145
	v_xor_b32_e32 v220, 64, v217

.LBB0_362:
	s_ashr_i32 s31, s30, 31
	v_cmp_lt_i64_e32 vcc, s[10:11], v[176:177]
	s_lshl_b64 s[10:11], s[30:31], 20
	s_add_u32 s34, s80, s10
	s_addc_u32 s35, s81, s11
	s_and_b64 s[10:11], vcc, exec
	s_cselect_b32 s31, s35, s7
	s_cselect_b32 s33, s34, s6
	s_ashr_i32 s29, s28, 31
	s_lshl_b64 s[10:11], s[28:29], 19
	s_add_u32 s36, s40, s10
	s_addc_u32 s37, s41, s11
	s_and_b64 s[10:11], vcc, exec
	s_cselect_b32 s29, s37, s9
	s_cselect_b32 s62, s36, s8
	s_add_u32 s63, s8, 0x100
	v_mov_b32_e32 v0, 0
	s_addc_u32 s64, s9, 0
	s_mov_b32 s65, -2
	v_mov_b32_e32 v1, v0
	v_mov_b64_e32 v[2:3], 0
	v_mov_b64_e32 v[64:65], 0
	v_mov_b64_e32 v[66:67], 0
	v_mov_b64_e32 v[8:9], 0
	s_waitcnt vmcnt(0)
	v_mov_b64_e32 v[10:11], 0
	v_mov_b64_e32 v[68:69], 0
	v_mov_b64_e32 v[70:71], 0
	v_mov_b64_e32 v[12:13], 0
	v_mov_b64_e32 v[14:15], 0
	v_mov_b64_e32 v[110:111], 0
	v_mov_b64_e32 v[112:113], 0
	v_mov_b64_e32 v[16:17], 0
	v_mov_b64_e32 v[18:19], 0
	v_mov_b64_e32 v[118:119], 0
	v_mov_b64_e32 v[120:121], 0
	v_mov_b64_e32 v[4:5], 0
	v_mov_b64_e32 v[6:7], 0
	v_mov_b64_e32 v[72:73], 0
	v_mov_b64_e32 v[74:75], 0
	v_mov_b64_e32 v[20:21], 0
	v_mov_b64_e32 v[22:23], 0
	v_mov_b64_e32 v[114:115], 0
	v_mov_b64_e32 v[116:117], 0
	v_mov_b64_e32 v[24:25], 0
	v_mov_b64_e32 v[26:27], 0
	v_mov_b64_e32 v[122:123], 0
	v_mov_b64_e32 v[124:125], 0
	v_mov_b64_e32 v[28:29], 0
	v_mov_b64_e32 v[30:31], 0
	v_mov_b64_e32 v[126:127], 0
	v_mov_b64_e32 v[128:129], 0
	v_mov_b64_e32 v[32:33], 0
	v_mov_b64_e32 v[34:35], 0
	v_mov_b64_e32 v[130:131], 0
	v_mov_b64_e32 v[132:133], 0
	v_mov_b64_e32 v[36:37], 0
	v_mov_b64_e32 v[38:39], 0
	v_mov_b64_e32 v[134:135], 0
	v_mov_b64_e32 v[136:137], 0
	v_mov_b64_e32 v[44:45], 0
	v_mov_b64_e32 v[46:47], 0
	v_mov_b64_e32 v[142:143], 0
	v_mov_b64_e32 v[144:145], 0
	v_mov_b64_e32 v[56:57], 0
	v_mov_b64_e32 v[58:59], 0
	v_mov_b64_e32 v[154:155], 0
	v_mov_b64_e32 v[156:157], 0
	v_mov_b64_e32 v[40:41], 0
	v_mov_b64_e32 v[42:43], 0
	v_mov_b64_e32 v[138:139], 0
	v_mov_b64_e32 v[140:141], 0
	v_mov_b64_e32 v[48:49], 0
	v_mov_b64_e32 v[50:51], 0
	v_mov_b64_e32 v[146:147], 0
	v_mov_b64_e32 v[148:149], 0
	v_mov_b64_e32 v[52:53], 0
	v_mov_b64_e32 v[54:55], 0
	v_mov_b64_e32 v[150:151], 0
	v_mov_b64_e32 v[152:153], 0
	v_mov_b64_e32 v[60:61], 0
	v_mov_b64_e32 v[62:63], 0
	v_mov_b64_e32 v[158:159], 0
	v_mov_b64_e32 v[160:161], 0
	v_xor_b32_e32 v216, 64, v231
	v_xor_b32_e32 v217, 64, v241
	v_xor_b32_e32 v244, 64, v242
	v_add_u32_e32 v245, 0x18000, v229
	v_xor_b32_e32 v246, 64, v245
	v_add_u32_e32 v247, 0x1c000, v229
	v_xor_b32_e32 v248, 64, v247

.LBB0_507:
	s_add_u32 s0, s0, 0x160080
	s_addc_u32 s1, s1, 0
	s_add_u32 s39, s16, 0x100
	v_mov_b32_e32 v0, 0
	s_addc_u32 s40, s17, 0
	s_mov_b32 s41, -2
	s_waitcnt lgkmcnt(0)
	v_mov_b32_e32 v1, v0
	v_mov_b64_e32 v[2:3], 0
	v_mov_b64_e32 v[4:5], 0
	v_mov_b64_e32 v[6:7], 0
	s_waitcnt vmcnt(0)
	v_mov_b64_e32 v[16:17], 0
	v_mov_b64_e32 v[18:19], 0
	v_mov_b64_e32 v[20:21], 0
	v_mov_b64_e32 v[22:23], 0
	v_mov_b64_e32 v[32:33], 0
	v_mov_b64_e32 v[34:35], 0
	v_mov_b64_e32 v[36:37], 0
	v_mov_b64_e32 v[38:39], 0
	v_mov_b64_e32 v[48:49], 0
	v_mov_b64_e32 v[50:51], 0
	v_mov_b64_e32 v[52:53], 0
	v_mov_b64_e32 v[54:55], 0
	v_mov_b64_e32 v[8:9], 0
	v_mov_b64_e32 v[10:11], 0
	v_mov_b64_e32 v[12:13], 0
	v_mov_b64_e32 v[14:15], 0
	v_mov_b64_e32 v[24:25], 0
	v_mov_b64_e32 v[26:27], 0
	v_mov_b64_e32 v[28:29], 0
	v_mov_b64_e32 v[30:31], 0
	v_mov_b64_e32 v[40:41], 0
	v_mov_b64_e32 v[42:43], 0
	v_mov_b64_e32 v[44:45], 0
	v_mov_b64_e32 v[46:47], 0
	v_mov_b64_e32 v[56:57], 0
	v_mov_b64_e32 v[58:59], 0
	v_mov_b64_e32 v[60:61], 0
	v_mov_b64_e32 v[62:63], 0
	v_mov_b64_e32 v[64:65], 0
	v_mov_b64_e32 v[66:67], 0
	v_mov_b64_e32 v[68:69], 0
	v_mov_b64_e32 v[70:71], 0
	v_mov_b64_e32 v[80:81], 0
	v_mov_b64_e32 v[82:83], 0
	v_mov_b64_e32 v[84:85], 0
	v_mov_b64_e32 v[86:87], 0
	v_mov_b64_e32 v[96:97], 0
	v_mov_b64_e32 v[98:99], 0
	v_mov_b64_e32 v[100:101], 0
	v_mov_b64_e32 v[102:103], 0
	v_mov_b64_e32 v[112:113], 0
	v_mov_b64_e32 v[114:115], 0
	v_mov_b64_e32 v[116:117], 0
	v_mov_b64_e32 v[118:119], 0
	v_mov_b64_e32 v[72:73], 0
	v_mov_b64_e32 v[74:75], 0
	v_mov_b64_e32 v[76:77], 0
	v_mov_b64_e32 v[78:79], 0
	v_mov_b64_e32 v[88:89], 0
	v_mov_b64_e32 v[90:91], 0
	v_mov_b64_e32 v[92:93], 0
	v_mov_b64_e32 v[94:95], 0
	v_mov_b64_e32 v[104:105], 0
	v_mov_b64_e32 v[106:107], 0
	v_mov_b64_e32 v[108:109], 0
	v_mov_b64_e32 v[110:111], 0
	v_mov_b64_e32 v[120:121], 0
	v_mov_b64_e32 v[122:123], 0
	v_mov_b64_e32 v[124:125], 0
	v_mov_b64_e32 v[126:127], 0
	v_xor_b32_e32 v216, 64, v141
	v_xor_b32_e32 v217, 64, v142
	v_xor_b32_e32 v244, 64, v143
	v_add_u32_e32 v245, 0x18000, v140
	v_xor_b32_e32 v246, 64, v245

.LBB0_598:
	s_ashr_i32 s21, s20, 31
	v_cmp_lt_i64_e32 vcc, s[22:23], v[136:137]
	s_lshl_b64 s[22:23], s[20:21], 20
	s_add_u32 s22, s80, s22
	s_addc_u32 s23, s81, s23
	s_and_b64 s[24:25], vcc, exec
	s_cselect_b32 s1, s23, s27
	s_cselect_b32 s13, s22, s26
	s_ashr_i32 s19, s18, 31
	s_lshl_b64 s[24:25], s[18:19], 20
	s_add_u32 s24, s34, s24
	s_addc_u32 s25, s35, s25
	s_and_b64 s[30:31], vcc, exec
	s_cselect_b32 s19, s25, s29
	s_cselect_b32 s21, s24, s28
	s_add_u32 s26, s26, 0x80080
	s_addc_u32 s27, s27, 0
	s_add_u32 s33, s28, 0x100
	v_mov_b32_e32 v0, 0
	s_addc_u32 s48, s29, 0
	s_mov_b32 s49, -2
	s_waitcnt lgkmcnt(0)
	v_mov_b32_e32 v1, v0
	v_mov_b64_e32 v[2:3], 0
	v_mov_b64_e32 v[4:5], 0
	v_mov_b64_e32 v[6:7], 0
	s_waitcnt vmcnt(0)
	v_mov_b64_e32 v[16:17], 0
	v_mov_b64_e32 v[18:19], 0
	v_mov_b64_e32 v[20:21], 0
	v_mov_b64_e32 v[22:23], 0
	v_mov_b64_e32 v[32:33], 0
	v_mov_b64_e32 v[34:35], 0
	v_mov_b64_e32 v[36:37], 0
	v_mov_b64_e32 v[38:39], 0
	v_mov_b64_e32 v[48:49], 0
	v_mov_b64_e32 v[50:51], 0
	v_mov_b64_e32 v[52:53], 0
	v_mov_b64_e32 v[54:55], 0
	v_mov_b64_e32 v[8:9], 0
	v_mov_b64_e32 v[10:11], 0
	v_mov_b64_e32 v[12:13], 0
	v_mov_b64_e32 v[14:15], 0
	v_mov_b64_e32 v[24:25], 0
	v_mov_b64_e32 v[26:27], 0
	v_mov_b64_e32 v[28:29], 0
	v_mov_b64_e32 v[30:31], 0
	v_mov_b64_e32 v[40:41], 0
	v_mov_b64_e32 v[42:43], 0
	v_mov_b64_e32 v[44:45], 0
	v_mov_b64_e32 v[46:47], 0
	v_mov_b64_e32 v[56:57], 0
	v_mov_b64_e32 v[58:59], 0
	v_mov_b64_e32 v[60:61], 0
	v_mov_b64_e32 v[62:63], 0
	v_mov_b64_e32 v[64:65], 0
	v_mov_b64_e32 v[66:67], 0
	v_mov_b64_e32 v[68:69], 0
	v_mov_b64_e32 v[70:71], 0
	v_mov_b64_e32 v[80:81], 0
	v_mov_b64_e32 v[82:83], 0
	v_mov_b64_e32 v[84:85], 0
	v_mov_b64_e32 v[86:87], 0
	v_mov_b64_e32 v[96:97], 0
	v_mov_b64_e32 v[98:99], 0
	v_mov_b64_e32 v[100:101], 0
	v_mov_b64_e32 v[102:103], 0
	v_mov_b64_e32 v[112:113], 0
	v_mov_b64_e32 v[114:115], 0
	v_mov_b64_e32 v[116:117], 0
	v_mov_b64_e32 v[118:119], 0
	v_mov_b64_e32 v[72:73], 0
	v_mov_b64_e32 v[74:75], 0
	v_mov_b64_e32 v[76:77], 0
	v_mov_b64_e32 v[78:79], 0
	v_mov_b64_e32 v[88:89], 0
	v_mov_b64_e32 v[90:91], 0
	v_mov_b64_e32 v[92:93], 0
	v_mov_b64_e32 v[94:95], 0
	v_mov_b64_e32 v[104:105], 0
	v_mov_b64_e32 v[106:107], 0
	v_mov_b64_e32 v[108:109], 0
	v_mov_b64_e32 v[110:111], 0
	v_mov_b64_e32 v[120:121], 0
	v_mov_b64_e32 v[122:123], 0
	v_mov_b64_e32 v[124:125], 0
	v_mov_b64_e32 v[126:127], 0
	v_xor_b32_e32 v144, 64, v149
	v_xor_b32_e32 v145, 64, v150
	v_xor_b32_e32 v216, 64, v151
	v_add_u32_e32 v217, 0x18000, v147
	v_xor_b32_e32 v234, 64, v217
	v_add_u32_e32 v235, 0x1c000, v147
	v_xor_b32_e32 v252, 64, v235

.LBB0_759:
	s_ashr_i32 s15, s14, 31
	v_cmp_lt_i64_e32 vcc, s[16:17], v[136:137]
	s_lshl_b64 s[16:17], s[14:15], 21
	s_add_u32 s16, s96, s16
	s_addc_u32 s17, s97, s17
	s_and_b64 s[18:19], vcc, exec
	s_cselect_b32 s1, s17, s21
	s_cselect_b32 s9, s16, s20
	s_ashr_i32 s13, s12, 31
	s_lshl_b64 s[18:19], s[12:13], 20
	s_add_u32 s18, s26, s18
	s_addc_u32 s19, s27, s19
	s_and_b64 s[24:25], vcc, exec
	s_cselect_b32 s13, s19, s23
	s_cselect_b32 s15, s18, s22
	s_add_u32 s20, s20, 0x100080
	s_addc_u32 s21, s21, 0
	s_add_u32 s43, s22, 0x100
	v_mov_b32_e32 v0, 0
	s_addc_u32 s44, s23, 0
	s_mov_b32 s45, -2
	s_waitcnt lgkmcnt(0)
	v_mov_b32_e32 v1, v0
	v_mov_b64_e32 v[2:3], 0
	v_mov_b64_e32 v[4:5], 0
	v_mov_b64_e32 v[6:7], 0
	s_waitcnt vmcnt(0)
	v_mov_b64_e32 v[16:17], 0
	v_mov_b64_e32 v[18:19], 0
	v_mov_b64_e32 v[20:21], 0
	v_mov_b64_e32 v[22:23], 0
	v_mov_b64_e32 v[32:33], 0
	v_mov_b64_e32 v[34:35], 0
	v_mov_b64_e32 v[36:37], 0
	v_mov_b64_e32 v[38:39], 0
	v_mov_b64_e32 v[48:49], 0
	v_mov_b64_e32 v[50:51], 0
	v_mov_b64_e32 v[52:53], 0
	v_mov_b64_e32 v[54:55], 0
	v_mov_b64_e32 v[8:9], 0
	v_mov_b64_e32 v[10:11], 0
	v_mov_b64_e32 v[12:13], 0
	v_mov_b64_e32 v[14:15], 0
	v_mov_b64_e32 v[24:25], 0
	v_mov_b64_e32 v[26:27], 0
	v_mov_b64_e32 v[28:29], 0
	v_mov_b64_e32 v[30:31], 0
	v_mov_b64_e32 v[40:41], 0
	v_mov_b64_e32 v[42:43], 0
	v_mov_b64_e32 v[44:45], 0
	v_mov_b64_e32 v[46:47], 0
	v_mov_b64_e32 v[56:57], 0
	v_mov_b64_e32 v[58:59], 0
	v_mov_b64_e32 v[60:61], 0
	v_mov_b64_e32 v[62:63], 0
	v_mov_b64_e32 v[64:65], 0
	v_mov_b64_e32 v[66:67], 0
	v_mov_b64_e32 v[68:69], 0
	v_mov_b64_e32 v[70:71], 0
	v_mov_b64_e32 v[80:81], 0
	v_mov_b64_e32 v[82:83], 0
	v_mov_b64_e32 v[84:85], 0
	v_mov_b64_e32 v[86:87], 0
	v_mov_b64_e32 v[96:97], 0
	v_mov_b64_e32 v[98:99], 0
	v_mov_b64_e32 v[100:101], 0
	v_mov_b64_e32 v[102:103], 0
	v_mov_b64_e32 v[112:113], 0
	v_mov_b64_e32 v[114:115], 0
	v_mov_b64_e32 v[116:117], 0
	v_mov_b64_e32 v[118:119], 0
	v_mov_b64_e32 v[72:73], 0
	v_mov_b64_e32 v[74:75], 0
	v_mov_b64_e32 v[76:77], 0
	v_mov_b64_e32 v[78:79], 0
	v_mov_b64_e32 v[88:89], 0
	v_mov_b64_e32 v[90:91], 0
	v_mov_b64_e32 v[92:93], 0
	v_mov_b64_e32 v[94:95], 0
	v_mov_b64_e32 v[104:105], 0
	v_mov_b64_e32 v[106:107], 0
	v_mov_b64_e32 v[108:109], 0
	v_mov_b64_e32 v[110:111], 0
	v_mov_b64_e32 v[120:121], 0
	v_mov_b64_e32 v[122:123], 0
	v_mov_b64_e32 v[124:125], 0
	v_mov_b64_e32 v[126:127], 0
	v_xor_b32_e32 v216, 64, v145
	v_xor_b32_e32 v217, 64, v146
	v_xor_b32_e32 v234, 64, v147
	v_add_u32_e32 v235, 0x18000, v144
	v_xor_b32_e32 v244, 64, v235

.LBB0_839:
	s_ashr_i32 s37, s36, 31
	v_cmp_lt_i64_e32 vcc, s[12:13], v[184:185]
	s_lshl_b64 s[12:13], s[36:37], 20
	s_add_u32 s38, s80, s12
	s_addc_u32 s39, s81, s13
	s_and_b64 s[12:13], vcc, exec
	s_cselect_b32 s33, s39, s9
	s_cselect_b32 s37, s38, s8
	s_ashr_i32 s35, s34, 31
	s_lshl_b64 s[12:13], s[34:35], 19
	s_add_u32 s40, s44, s12
	s_addc_u32 s41, s45, s13
	s_and_b64 s[12:13], vcc, exec
	s_cselect_b32 s35, s41, s11
	s_cselect_b32 s64, s40, s10
	s_add_u32 s65, s10, 0x100
	v_mov_b32_e32 v0, 0
	s_addc_u32 s66, s11, 0
	s_mov_b32 s67, -2
	v_mov_b32_e32 v1, v0
	v_mov_b64_e32 v[2:3], 0
	v_mov_b64_e32 v[64:65], 0
	v_mov_b64_e32 v[66:67], 0
	v_mov_b64_e32 v[8:9], 0
	s_waitcnt vmcnt(0)
	v_mov_b64_e32 v[10:11], 0
	v_mov_b64_e32 v[68:69], 0
	v_mov_b64_e32 v[70:71], 0
	v_mov_b64_e32 v[12:13], 0
	v_mov_b64_e32 v[14:15], 0
	v_mov_b64_e32 v[110:111], 0
	v_mov_b64_e32 v[112:113], 0
	v_mov_b64_e32 v[16:17], 0
	v_mov_b64_e32 v[18:19], 0
	v_mov_b64_e32 v[118:119], 0
	v_mov_b64_e32 v[120:121], 0
	v_mov_b64_e32 v[4:5], 0
	v_mov_b64_e32 v[6:7], 0
	v_mov_b64_e32 v[72:73], 0
	v_mov_b64_e32 v[74:75], 0
	v_mov_b64_e32 v[20:21], 0
	v_mov_b64_e32 v[22:23], 0
	v_mov_b64_e32 v[114:115], 0
	v_mov_b64_e32 v[116:117], 0
	v_mov_b64_e32 v[24:25], 0
	v_mov_b64_e32 v[26:27], 0
	v_mov_b64_e32 v[122:123], 0
	v_mov_b64_e32 v[124:125], 0
	v_mov_b64_e32 v[28:29], 0
	v_mov_b64_e32 v[30:31], 0
	v_mov_b64_e32 v[126:127], 0
	v_mov_b64_e32 v[128:129], 0
	v_mov_b64_e32 v[32:33], 0
	v_mov_b64_e32 v[34:35], 0
	v_mov_b64_e32 v[130:131], 0
	v_mov_b64_e32 v[132:133], 0
	v_mov_b64_e32 v[36:37], 0
	v_mov_b64_e32 v[38:39], 0
	v_mov_b64_e32 v[134:135], 0
	v_mov_b64_e32 v[136:137], 0
	v_mov_b64_e32 v[44:45], 0
	v_mov_b64_e32 v[46:47], 0
	v_mov_b64_e32 v[142:143], 0
	v_mov_b64_e32 v[144:145], 0
	v_mov_b64_e32 v[56:57], 0
	v_mov_b64_e32 v[58:59], 0
	v_mov_b64_e32 v[154:155], 0
	v_mov_b64_e32 v[156:157], 0
	v_mov_b64_e32 v[40:41], 0
	v_mov_b64_e32 v[42:43], 0
	v_mov_b64_e32 v[138:139], 0
	v_mov_b64_e32 v[140:141], 0
	v_mov_b64_e32 v[48:49], 0
	v_mov_b64_e32 v[50:51], 0
	v_mov_b64_e32 v[146:147], 0
	v_mov_b64_e32 v[148:149], 0
	v_mov_b64_e32 v[52:53], 0
	v_mov_b64_e32 v[54:55], 0
	v_mov_b64_e32 v[150:151], 0
	v_mov_b64_e32 v[152:153], 0
	v_mov_b64_e32 v[60:61], 0
	v_mov_b64_e32 v[62:63], 0
	v_mov_b64_e32 v[158:159], 0
	v_mov_b64_e32 v[160:161], 0
	v_xor_b32_e32 v220, 64, v171
	v_xor_b32_e32 v221, 64, v173
	v_xor_b32_e32 v238, 64, v175
	v_add_u32_e32 v239, 0x18000, v169
	v_xor_b32_e32 v240, 64, v239
	v_add_u32_e32 v241, 0x1c000, v169
	v_xor_b32_e32 v242, 64, v241

.LBB0_984:
	s_add_u32 s0, s0, 0x160080
	s_addc_u32 s1, s1, 0
	s_add_u32 s39, s14, 0x100
	v_mov_b32_e32 v0, 0
	s_addc_u32 s40, s15, 0
	s_mov_b32 s41, -2
	s_waitcnt lgkmcnt(0)
	v_mov_b32_e32 v1, v0
	v_mov_b64_e32 v[2:3], 0
	v_mov_b64_e32 v[4:5], 0
	v_mov_b64_e32 v[6:7], 0
	s_waitcnt vmcnt(0)
	v_mov_b64_e32 v[16:17], 0
	v_mov_b64_e32 v[18:19], 0
	v_mov_b64_e32 v[20:21], 0
	v_mov_b64_e32 v[22:23], 0
	v_mov_b64_e32 v[32:33], 0
	v_mov_b64_e32 v[34:35], 0
	v_mov_b64_e32 v[36:37], 0
	v_mov_b64_e32 v[38:39], 0
	v_mov_b64_e32 v[48:49], 0
	v_mov_b64_e32 v[50:51], 0
	v_mov_b64_e32 v[52:53], 0
	v_mov_b64_e32 v[54:55], 0
	v_mov_b64_e32 v[8:9], 0
	v_mov_b64_e32 v[10:11], 0
	v_mov_b64_e32 v[12:13], 0
	v_mov_b64_e32 v[14:15], 0
	v_mov_b64_e32 v[24:25], 0
	v_mov_b64_e32 v[26:27], 0
	v_mov_b64_e32 v[28:29], 0
	v_mov_b64_e32 v[30:31], 0
	v_mov_b64_e32 v[40:41], 0
	v_mov_b64_e32 v[42:43], 0
	v_mov_b64_e32 v[44:45], 0
	v_mov_b64_e32 v[46:47], 0
	v_mov_b64_e32 v[56:57], 0
	v_mov_b64_e32 v[58:59], 0
	v_mov_b64_e32 v[60:61], 0
	v_mov_b64_e32 v[62:63], 0
	v_mov_b64_e32 v[64:65], 0
	v_mov_b64_e32 v[66:67], 0
	v_mov_b64_e32 v[68:69], 0
	v_mov_b64_e32 v[70:71], 0
	v_mov_b64_e32 v[80:81], 0
	v_mov_b64_e32 v[82:83], 0
	v_mov_b64_e32 v[84:85], 0
	v_mov_b64_e32 v[86:87], 0
	v_mov_b64_e32 v[96:97], 0
	v_mov_b64_e32 v[98:99], 0
	v_mov_b64_e32 v[100:101], 0
	v_mov_b64_e32 v[102:103], 0
	v_mov_b64_e32 v[112:113], 0
	v_mov_b64_e32 v[114:115], 0
	v_mov_b64_e32 v[116:117], 0
	v_mov_b64_e32 v[118:119], 0
	v_mov_b64_e32 v[72:73], 0
	v_mov_b64_e32 v[74:75], 0
	v_mov_b64_e32 v[76:77], 0
	v_mov_b64_e32 v[78:79], 0
	v_mov_b64_e32 v[88:89], 0
	v_mov_b64_e32 v[90:91], 0
	v_mov_b64_e32 v[92:93], 0
	v_mov_b64_e32 v[94:95], 0
	v_mov_b64_e32 v[104:105], 0
	v_mov_b64_e32 v[106:107], 0
	v_mov_b64_e32 v[108:109], 0
	v_mov_b64_e32 v[110:111], 0
	v_mov_b64_e32 v[120:121], 0
	v_mov_b64_e32 v[122:123], 0
	v_mov_b64_e32 v[124:125], 0
	v_mov_b64_e32 v[126:127], 0
	v_xor_b32_e32 v216, 64, v141
	v_xor_b32_e32 v217, 64, v142
	v_xor_b32_e32 v218, 64, v143
	v_add_u32_e32 v219, 0x18000, v140
	v_xor_b32_e32 v220, 64, v219
